# MLA and SWA loops: single lgkmcnt wait for the second V batch, redundant add-of-zero and canonicalising max removed, one SALU fewer (bitwise identical)
# baseline (speedup 1.0000x reference)
.LBB0_466:
	s_nop 3
	v_max_f32_e32 v0, v34, v35
	v_max3_f32 v112, v36, v37, v51
	v_max3_f32 v0, v0, v50, v52
	v_max3_f32 v0, v0, v53, v38
	v_max3_f32 v112, v112, v40, v41
	v_max3_f32 v0, v0, v39, v54
	v_max3_f32 v112, v112, v56, v57
	v_max3_f32 v0, v0, v55, v42
	v_max3_f32 v112, v112, v44, v45
	v_max3_f32 v0, v0, v43, v58
	v_max3_f32 v112, v112, v60, v61
	v_max3_f32 v0, v0, v59, v46
	v_max3_f32 v112, v112, v48, v49
	v_max3_f32 v0, v0, v47, v62
	v_max3_f32 v112, v112, v64, v65
	v_and_b32_e32 v113, 64, v241
	v_max3_f32 v0, v0, v63, v112
	v_xor_b32_e32 v112, 32, v241
	v_add_u32_e32 v113, 64, v113
	v_cmp_lt_i32_e32 vcc, v112, v113
	s_nop 1
	v_cndmask_b32_e32 v115, v241, v112, vcc
	v_lshlrev_b32_e32 v115, 2, v115
	ds_bpermute_b32 v115, v115, v0
	s_waitcnt lgkmcnt(0)
	ds_read_b64_tr_b16 v[196:197], v234 offset:13376
	ds_read_b64_tr_b16 v[198:199], v234 offset:14912
	ds_read_b64_tr_b16 v[200:201], v234 offset:16448
	ds_read_b64_tr_b16 v[202:203], v234 offset:17984
	ds_read_b64_tr_b16 v[204:205], v234 offset:19520
	ds_read_b64_tr_b16 v[206:207], v234 offset:21056
	ds_read_b64_tr_b16 v[214:215], v234 offset:22592
	ds_read_b64_tr_b16 v[216:217], v234 offset:24128
	v_max_f32_e32 v115, v115, v115
	v_max_f32_e32 v0, v0, v115
	v_cmp_lt_f32_e32 vcc, s7, v0
	s_cbranch_vccz .LBB0_470
	v_max_f32_e32 v0, v0, v0
	v_max_f32_e32 v0, 0, v0
	v_add_f32_e32 v0, v114, v0
	v_cvt_pk_bf16_f32 v0, v0, v1
	s_nop 0
	v_lshlrev_b32_e32 v0, 16, v0
	s_and_saveexec_b64 s[10:11], s[36:37]
	s_cbranch_execz .LBB0_469
	v_xor_b32_e32 v115, 0x80000000, v0
	v_cvt_pk_bf16_f32 v115, v115, v1
	s_nop 0
	v_bfi_b32 v94, s2, v115, v94

.LBB0_471:
	v_exp_f32_e32 v34, v34
	v_exp_f32_e32 v35, v35
	v_exp_f32_e32 v36, v36
	v_exp_f32_e32 v37, v37
	v_exp_f32_e32 v38, v38
	v_exp_f32_e32 v39, v39
	v_exp_f32_e32 v40, v40
	v_exp_f32_e32 v41, v41
	v_cvt_pk_bf16_f32 v114, v34, v35
	v_cvt_pk_bf16_f32 v115, v36, v37
	v_cvt_pk_bf16_f32 v116, v38, v39
	v_cvt_pk_bf16_f32 v117, v40, v41
	v_exp_f32_e32 v42, v42
	v_exp_f32_e32 v43, v43
	v_mfma_f32_32x32x16_bf16 v[2:17], v[180:183], v[114:117], v[2:17]
	s_waitcnt lgkmcnt(0)
	v_mfma_f32_32x32x16_bf16 v[18:33], v[196:199], v[114:117], v[18:33]
	v_exp_f32_e32 v44, v44
	v_exp_f32_e32 v45, v45
	v_exp_f32_e32 v46, v46
	v_exp_f32_e32 v47, v47
	v_exp_f32_e32 v48, v48
	v_exp_f32_e32 v49, v49
	v_cvt_pk_bf16_f32 v122, v42, v43
	v_cvt_pk_bf16_f32 v123, v44, v45
	v_cvt_pk_bf16_f32 v124, v46, v47
	v_cvt_pk_bf16_f32 v125, v48, v49
	v_exp_f32_e32 v50, v50
	v_exp_f32_e32 v51, v51
	v_mfma_f32_32x32x16_bf16 v[2:17], v[184:187], v[122:125], v[2:17]
	v_mfma_f32_32x32x16_bf16 v[18:33], v[200:203], v[122:125], v[18:33]
	v_exp_f32_e32 v52, v52
	v_exp_f32_e32 v53, v53
	v_exp_f32_e32 v54, v54
	v_exp_f32_e32 v55, v55
	v_exp_f32_e32 v56, v56
	v_exp_f32_e32 v57, v57
	v_cvt_pk_bf16_f32 v118, v50, v51
	v_cvt_pk_bf16_f32 v119, v52, v53
	v_cvt_pk_bf16_f32 v120, v54, v55
	v_cvt_pk_bf16_f32 v121, v56, v57
	v_exp_f32_e32 v58, v58
	v_exp_f32_e32 v59, v59
	v_mfma_f32_32x32x16_bf16 v[2:17], v[188:191], v[118:121], v[2:17]
	v_mfma_f32_32x32x16_bf16 v[18:33], v[204:207], v[118:121], v[18:33]
	v_exp_f32_e32 v60, v60
	v_exp_f32_e32 v61, v61
	v_exp_f32_e32 v62, v62
	v_exp_f32_e32 v63, v63
	v_exp_f32_e32 v64, v64
	v_exp_f32_e32 v65, v65
	v_cvt_pk_bf16_f32 v126, v58, v59
	v_cvt_pk_bf16_f32 v127, v60, v61
	v_cvt_pk_bf16_f32 v128, v62, v63
	v_cvt_pk_bf16_f32 v129, v64, v65
	s_nop 1
	v_mfma_f32_32x32x16_bf16 v[2:17], v[192:195], v[126:129], v[2:17]
	v_mfma_f32_32x32x16_bf16 v[18:33], v[214:217], v[126:129], v[18:33]
	s_andn2_b64 vcc, exec, s[16:17]
	s_cbranch_vccnz .LBB0_473
	s_bitcmp1_b32 s18, 0
	s_cselect_b32 s10, 0x6400, 0
	s_add_i32 s10, s10, 0
	v_add_u32_e32 v115, s10, v106
	v_add_u32_e32 v114, s10, v107
	s_waitcnt vmcnt(1)
	ds_write_b128 v115, v[86:89]
	s_waitcnt vmcnt(0)
	ds_write_b128 v114, v[90:93] offset:13312
.LBB0_473:
	v_add_f32_e32 v34, v50, v34
	v_add_f32_e32 v35, v51, v35
	v_add_f32_e32 v36, v52, v36
	v_add_f32_e32 v34, v35, v34
	v_add_f32_e32 v37, v53, v37
	v_add_f32_e32 v34, v36, v34
	v_add_f32_e32 v38, v54, v38
	v_add_f32_e32 v34, v37, v34
	v_add_f32_e32 v39, v55, v39
	v_add_f32_e32 v34, v38, v34
	v_add_f32_e32 v40, v56, v40
	v_add_f32_e32 v34, v39, v34
	v_add_f32_e32 v41, v57, v41
	v_add_f32_e32 v34, v40, v34
	v_add_f32_e32 v42, v58, v42
	v_add_f32_e32 v34, v41, v34
	v_add_f32_e32 v43, v59, v43
	v_add_f32_e32 v34, v42, v34
	v_add_f32_e32 v44, v60, v44
	v_add_f32_e32 v34, v43, v34
	v_add_f32_e32 v45, v61, v45
	v_add_f32_e32 v34, v44, v34
	v_add_f32_e32 v46, v62, v46
	v_add_f32_e32 v34, v45, v34
	v_add_f32_e32 v47, v63, v47
	v_add_f32_e32 v34, v46, v34
	v_add_f32_e32 v48, v64, v48
	v_add_f32_e32 v34, v47, v34
	v_add_f32_e32 v49, v65, v49
	v_add_f32_e32 v34, v48, v34
	v_add_f32_e32 v34, v49, v34
	v_add_f32_e32 v101, v101, v34
	v_subrev_u32_e32 v110, 64, v110
	s_cmp_lg_u32 s38, s18
	v_add_u32_e32 v111, 64, v111
	s_waitcnt lgkmcnt(0)
	s_barrier
	s_cbranch_scc0 .LBB0_476
	v_mov_b32_e32 v114, v0
	s_mov_b32 s10, s18
	s_branch .Lswa4_top

.LBB0_498:
	s_or_b64 exec, exec, s[10:11]
	s_nop 0
	s_waitcnt lgkmcnt(10)
	v_mfma_f32_32x32x16_bf16 v[34:49], v[148:151], v[74:77], v[218:233]
	v_mfma_f32_32x32x16_bf16 v[50:65], v[152:155], v[74:77], v[218:233]
	s_waitcnt lgkmcnt(8)
	v_mfma_f32_32x32x16_bf16 v[34:49], v[156:159], v[66:69], v[34:49]
	v_mfma_f32_32x32x16_bf16 v[50:65], v[160:163], v[66:69], v[50:65]
	s_waitcnt lgkmcnt(6)
	v_mfma_f32_32x32x16_bf16 v[34:49], v[164:167], v[82:85], v[34:49]
	v_mfma_f32_32x32x16_bf16 v[50:65], v[168:171], v[82:85], v[50:65]
	s_waitcnt lgkmcnt(4)
	v_mfma_f32_32x32x16_bf16 v[34:49], v[172:175], v[70:73], v[34:49]
	v_mfma_f32_32x32x16_bf16 v[50:65], v[176:179], v[70:73], v[50:65]
	s_waitcnt lgkmcnt(2)
	v_mfma_f32_32x32x16_bf16 v[34:49], v[180:183], v[86:89], v[34:49]
	v_mfma_f32_32x32x16_bf16 v[50:65], v[184:187], v[86:89], v[50:65]
	s_waitcnt lgkmcnt(0)
	v_mfma_f32_32x32x16_bf16 v[34:49], v[188:191], v[78:81], v[34:49]
	v_mfma_f32_32x32x16_bf16 v[50:65], v[192:195], v[78:81], v[50:65]
	ds_read_b64_tr_b16 v[196:197], v234 offset:13312
	ds_read_b64_tr_b16 v[198:199], v234 offset:14848
	ds_read_b64_tr_b16 v[200:201], v234 offset:16384
	ds_read_b64_tr_b16 v[202:203], v234 offset:17920
	ds_read_b64_tr_b16 v[204:205], v234 offset:19456
	ds_read_b64_tr_b16 v[206:207], v234 offset:20992
	ds_read_b64_tr_b16 v[214:215], v234 offset:22528
	ds_read_b64_tr_b16 v[216:217], v234 offset:24064
	s_nop 2
	v_max_f32_e32 v126, v34, v35
	v_max3_f32 v128, v36, v37, v51
	v_max3_f32 v126, v126, v50, v52
	v_max3_f32 v126, v126, v53, v38
	v_max3_f32 v128, v128, v40, v41
	v_max3_f32 v126, v126, v39, v54
	v_max3_f32 v128, v128, v56, v57
	v_max3_f32 v126, v126, v55, v42
	v_max3_f32 v128, v128, v44, v45
	v_max3_f32 v126, v126, v43, v58
	v_max3_f32 v128, v128, v60, v61
	v_max3_f32 v126, v126, v59, v46
	v_max3_f32 v128, v128, v48, v49
	v_max3_f32 v126, v126, v47, v62
	v_max3_f32 v128, v128, v64, v65
	v_max3_f32 v126, v126, v63, v128
	ds_bpermute_b32 v128, v113, v126
	s_waitcnt lgkmcnt(0)
	ds_read_b64_tr_b16 v[148:149], v234 offset:13376
	ds_read_b64_tr_b16 v[150:151], v234 offset:14912
	ds_read_b64_tr_b16 v[152:153], v234 offset:16448
	ds_read_b64_tr_b16 v[154:155], v234 offset:17984
	ds_read_b64_tr_b16 v[156:157], v234 offset:19520
	ds_read_b64_tr_b16 v[158:159], v234 offset:21056
	ds_read_b64_tr_b16 v[160:161], v234 offset:22592
	ds_read_b64_tr_b16 v[162:163], v234 offset:24128
	v_max_f32_e32 v128, v128, v128
	v_max_f32_e32 v126, v126, v128
	v_cmp_lt_f32_e32 vcc, s7, v126
	s_cbranch_vccz .LBB0_502
	v_max_f32_e32 v126, v126, v126
	v_max_f32_e32 v126, 0, v126
	v_add_f32_e32 v126, v127, v126
	v_cvt_pk_bf16_f32 v126, v126, v1
	s_nop 0
	v_lshlrev_b32_e32 v126, 16, v126
	s_and_saveexec_b64 s[10:11], s[36:37]
	s_cbranch_execz .LBB0_501
	v_xor_b32_e32 v128, 0x80000000, v126
	v_cvt_pk_bf16_f32 v128, v128, v1
	s_nop 0
	v_bfi_b32 v98, s2, v128, v98

.LBB0_503:
	v_exp_f32_e32 v34, v34
	v_exp_f32_e32 v35, v35
	v_exp_f32_e32 v36, v36
	v_exp_f32_e32 v37, v37
	v_exp_f32_e32 v38, v38
	v_exp_f32_e32 v39, v39
	v_exp_f32_e32 v40, v40
	v_exp_f32_e32 v41, v41
	v_cvt_pk_bf16_f32 v128, v34, v35
	v_cvt_pk_bf16_f32 v129, v36, v37
	v_cvt_pk_bf16_f32 v130, v38, v39
	v_cvt_pk_bf16_f32 v131, v40, v41
	v_exp_f32_e32 v42, v42
	v_exp_f32_e32 v43, v43
	v_mfma_f32_32x32x16_bf16 v[2:17], v[196:199], v[128:131], v[2:17]
	s_waitcnt lgkmcnt(0)
	v_mfma_f32_32x32x16_bf16 v[18:33], v[148:151], v[128:131], v[18:33]
	v_exp_f32_e32 v44, v44
	v_exp_f32_e32 v45, v45
	v_exp_f32_e32 v46, v46
	v_exp_f32_e32 v47, v47
	v_exp_f32_e32 v48, v48
	v_exp_f32_e32 v49, v49
	v_cvt_pk_bf16_f32 v136, v42, v43
	v_cvt_pk_bf16_f32 v137, v44, v45
	v_cvt_pk_bf16_f32 v138, v46, v47
	v_cvt_pk_bf16_f32 v139, v48, v49
	v_exp_f32_e32 v50, v50
	v_exp_f32_e32 v51, v51
	v_mfma_f32_32x32x16_bf16 v[2:17], v[200:203], v[136:139], v[2:17]
	v_mfma_f32_32x32x16_bf16 v[18:33], v[152:155], v[136:139], v[18:33]
	v_exp_f32_e32 v52, v52
	v_exp_f32_e32 v53, v53
	v_exp_f32_e32 v54, v54
	v_exp_f32_e32 v55, v55
	v_exp_f32_e32 v56, v56
	v_exp_f32_e32 v57, v57
	v_cvt_pk_bf16_f32 v132, v50, v51
	v_cvt_pk_bf16_f32 v133, v52, v53
	v_cvt_pk_bf16_f32 v134, v54, v55
	v_cvt_pk_bf16_f32 v135, v56, v57
	v_exp_f32_e32 v58, v58
	v_exp_f32_e32 v59, v59
	v_mfma_f32_32x32x16_bf16 v[2:17], v[204:207], v[132:135], v[2:17]
	v_mfma_f32_32x32x16_bf16 v[18:33], v[156:159], v[132:135], v[18:33]
	v_exp_f32_e32 v60, v60
	v_exp_f32_e32 v61, v61
	v_exp_f32_e32 v62, v62
	v_exp_f32_e32 v63, v63
	v_exp_f32_e32 v64, v64
	v_exp_f32_e32 v65, v65
	v_cvt_pk_bf16_f32 v140, v58, v59
	v_cvt_pk_bf16_f32 v141, v60, v61
	v_cvt_pk_bf16_f32 v142, v62, v63
	v_cvt_pk_bf16_f32 v143, v64, v65
	s_bitcmp1_b32 s17, 0
	s_cselect_b32 s17, 0x6400, 0
	v_mfma_f32_32x32x16_bf16 v[2:17], v[214:217], v[140:143], v[2:17]
	v_mfma_f32_32x32x16_bf16 v[18:33], v[160:163], v[140:143], v[18:33]
	v_add_u32_e32 v238, s17, v120
	v_add_u32_e32 v239, s17, v121
	s_waitcnt vmcnt(1)
	ds_write_b128 v238, v[106:109]
	s_waitcnt vmcnt(0)
	ds_write_b128 v239, v[102:105] offset:13312
	s_and_saveexec_b64 s[10:11], s[38:39]
	v_add3_u32 v238, s17, v112, v122
	ds_write_b128 v238, v[94:97] offset:128
	s_or_b64 exec, exec, s[10:11]
	v_add_f32_e32 v34, v50, v34
	v_add_f32_e32 v35, v51, v35
	v_add_f32_e32 v36, v52, v36
	v_add_f32_e32 v34, v35, v34
	v_add_f32_e32 v37, v53, v37
	v_add_f32_e32 v34, v36, v34
	v_add_f32_e32 v38, v54, v38
	v_add_f32_e32 v34, v37, v34
	v_add_f32_e32 v39, v55, v39
	v_add_f32_e32 v34, v38, v34
	v_add_f32_e32 v40, v56, v40
	v_add_f32_e32 v34, v39, v34
	v_add_f32_e32 v41, v57, v41
	v_add_f32_e32 v34, v40, v34
	v_add_f32_e32 v42, v58, v42
	v_add_f32_e32 v34, v41, v34
	v_add_f32_e32 v43, v59, v43
	v_add_f32_e32 v34, v42, v34
	v_add_f32_e32 v44, v60, v44
	v_add_f32_e32 v34, v43, v34
	v_add_f32_e32 v45, v61, v45
	v_add_f32_e32 v34, v44, v34
	v_add_f32_e32 v46, v62, v46
	v_add_f32_e32 v34, v45, v34
	v_add_f32_e32 v47, v63, v47
	v_add_f32_e32 v34, v46, v34
	v_add_f32_e32 v48, v64, v48
	v_add_f32_e32 v34, v47, v34
	v_add_f32_e32 v49, v65, v49
	v_add_f32_e32 v34, v48, v34
	v_add_f32_e32 v34, v49, v34
	v_add_f32_e32 v119, v119, v34
	v_add_u32_e32 v124, 64, v124
	s_cmp_lg_u32 s16, s15
	v_add_u32_e32 v125, 64, v125
	s_waitcnt lgkmcnt(0)
	s_barrier
	s_cbranch_scc0 .LBB0_507
	v_mov_b32_e32 v127, v126
	s_branch .Lmla4_top
